# v062 + MERGE start offset moved to the workgroups that have no tail half-unit (bid >= 128; last layer keeps odd bids), so the offset no longer extends the phase
# baseline (speedup 1.0000x reference)
.LBB0_1053:
	s_waitcnt lgkmcnt(0)
	s_barrier
	v_mbcnt_lo_u32_b32 v0, -1, 0
	v_mbcnt_hi_u32_b32 v0, -1, v0
	v_readlane_b32 s42, v255, 11
	s_mov_b32 s2, s55
	v_readlane_b32 s48, v255, 12
	s_mov_b32 s43, s84
	v_readlane_b32 s4, v255, 4
	v_readlane_b32 s6, v255, 6
	v_readlane_b32 s7, v255, 7
	s_and_b32 s41, s43, 1
	s_lshr_b32 s98, s43, 7
	s_cmp_eq_u32 s2, 3
	s_cselect_b32 s98, s41, s98
	s_mov_b32 s10, s6
	s_mov_b32 s11, s7
	s_cmp_eq_u32 s98, 0
	v_readlane_b32 s5, v255, 5
	s_cbranch_scc1 .LBB0_1056
	s_memrealtime s[4:5]
	s_memrealtime s[0:1]
	v_mov_b64_e32 v[2:3], 0x351
	s_waitcnt lgkmcnt(0)
	s_sub_u32 s0, s0, s4
	s_subb_u32 s1, s1, s5
	v_cmp_gt_u64_e32 vcc, s[0:1], v[2:3]
	s_cbranch_vccnz .LBB0_1056
